# scan_dn MFMA ring + four-class schedule of decode iterations and pass-C items
# speedup vs baseline: 1.0077x; 1.0077x over previous
.LBB0_553:
	v_writelane_b32 v238, s26, 27
	s_cmpk_lt_i32 s2, 0x220
	s_cselect_b64 s[4:5], -1, 0
	v_writelane_b32 v238, s27, 28
	v_writelane_b32 v238, s96, 29
	v_writelane_b32 v238, s4, 33
	s_cmpk_gt_i32 s2, 0x21f
	s_nop 0
	v_writelane_b32 v238, s5, 34
	s_cbranch_scc1 .LBB0_618
	s_add_u32 s12, s28, 0x90fe040
	s_addc_u32 s13, s29, 0
	s_add_u32 s20, s30, 0x10e00800
	s_addc_u32 s21, s31, 0
	s_add_u32 s22, s28, 0x50fe040
	s_addc_u32 s23, s29, 0
	s_add_u32 s24, s30, 0x10e00000
	v_mbcnt_lo_u32_b32 v0, -1, 0
	v_readlane_b32 s4, v238, 27
	s_addc_u32 s25, s31, 0
	s_mov_b32 s17, 0xa000
	s_movk_i32 s27, 0x2000
	v_mov_b32_e32 v17, 0
	s_movk_i32 s37, 0x3800
	s_movk_i32 s39, 0x3000
	v_mov_b32_e32 v177, 0x3ecc95a3
	s_movk_i32 s47, 0x1000
	s_movk_i32 s50, 0x4000
	s_movk_i32 s51, 0x5000
	s_movk_i32 s82, 0x6000
	s_movk_i32 s83, 0x7000
	s_mov_b32 s96, 0x8000
	s_mov_b32 s97, 0x9000
	s_mov_b32 s10, 0xb000
	s_mov_b32 s11, 0xc000
	s_mov_b32 s42, 0xd000
	s_mov_b32 s18, 0xe000
	s_mov_b32 s19, 0xf000
	s_mov_b32 s45, 0x1c000
	s_mov_b32 s46, 0x1d000
	s_mov_b32 s14, 0x1e000
	s_mov_b32 s26, 0x3b800000
	s_mov_b32 s36, 0x358637bd
	s_mov_b32 s43, 0x800000
	s_brev_b32 s38, 60
	v_mov_b32_e32 v184, 0x7f800000
	v_mov_b32_e32 v185, 0x7fc00000
	v_mov_b32_e32 v186, 0xff800000
	v_mbcnt_hi_u32_b32 v187, -1, v0
	v_mov_b32_e32 v18, 0x3f317218
	s_mov_b32 s44, s4
	s_mov_b32 s101, s16
	s_mov_b32 s100, 0x200
	v_readlane_b32 s5, v239, 2
	s_nop 0
	s_cmp_lg_u32 s5, 0x100
	s_cbranch_scc1 .Lsmp_done
	s_cmp_lt_i32 s4, 32
	s_cbranch_scc1 .Lsmp_x
	s_add_i32 s44, s4, 0xffffffe0
	s_mov_b32 s101, 0xc0
	s_cmp_lt_i32 s4, 0x60
	s_cbranch_scc1 .Lsmp_done
	s_mov_b32 s101, 0x100
	s_cmp_lt_i32 s4, 0xa0
	s_cbranch_scc1 .Lsmp_done
	s_mov_b32 s101, 0x140
	s_branch .Lsmp_done
.Lsmp_x:
	s_add_i32 s44, s4, 0x100
	s_mov_b32 s101, 32
	s_mov_b32 s100, 0x140
.Lsmp_done:
	v_readlane_b32 s5, v238, 28
	s_branch .LBB0_557

.LBB0_556:
	s_add_i32 s44, s44, s101
	s_cmp_ge_i32 s44, s100
	s_cbranch_scc1 .LBB0_618

.LBB0_635:
	s_or_b64 exec, exec, s[4:5]
	v_readlane_b32 s4, v238, 33
	v_readlane_b32 s5, v238, 34
	v_readlane_b32 s50, v238, 17
	s_andn2_b64 vcc, exec, s[4:5]
	v_readlane_b32 s51, v238, 18
	v_readlane_b32 s96, v238, 29
	s_barrier
	s_cbranch_vccnz .LBB0_662
	v_readlane_b32 s101, v239, 2
	s_mov_b32 s100, 0x200
	s_cmp_lg_u32 s101, 0x100
	s_cbranch_scc1 .Lrebal_done
	s_cmp_lt_i32 s68, 32
	s_cbranch_scc1 .Lrebal_x
	s_cmp_lt_i32 s68, 0x60
	s_cbranch_scc1 .Lrebal_y
	s_cmp_lt_i32 s68, 0xc0
	s_cbranch_scc1 .Lrebal_z
	s_add_i32 s68, s68, 0xe0
	s_mov_b32 s16, 32
	s_mov_b32 s100, 0x1e0
	s_branch .Lrebal_done
.Lrebal_x:
	s_add_i32 s68, s68, 0x1e0
	s_branch .Lrebal_done
.Lrebal_y:
	s_add_i32 s68, s68, 0x100
	s_mov_b32 s16, 64
	s_mov_b32 s100, 0x1a0
	s_branch .Lrebal_done
.Lrebal_z:
	s_add_i32 s68, s68, 0xffffffa0
	s_mov_b32 s16, 0x60
	s_mov_b32 s100, 0x120
